# prologue phase: hb=bf16(x) + row sum-squares loop rewritten by hand (all 32 row-chunk loads of a wave in flight, interleaved wave reductions)
# speedup vs baseline: 1.0017x; 1.0005x over previous
; DI void st_bf4(bf16_t* p, f32x4 v) { u32x2 w; w.x = pk2(v[0], v[1]); w.y = pk2(v[2], v[3]); *(u32x2*)p = w; }
;     DI bf16_t* hb() const { return (bf16_t*)(ws + WS_HB); }
;     DI float* ssqh() const { return (float*)(ws + WS_SSQH); }
;     DI const float* gin(int i) const { return (const float*)(const __attribute__((address_space(1))) float*)kp->in[i]; }
; DI void phase_prep(Frame& F) {
;     ...
;     for (int row = F.gw; row < M; row += F.ngw) {
;         const f32x4* xr = (const f32x4*)(F.gin(0) + (size_t)row * DM) + F.lane; float s = 0.f;
; #pragma unroll
;         for (int j = 0; j < 4; ++j) { f32x4 v = xr[64 * j]; s += (v[0] * v[0] + v[1] * v[1]) + (v[2] * v[2] + v[3] * v[3]);
;             st_bf4(F.hb() + (size_t)row * DM + 4 * (F.lane + 64 * j), v); }
;         s = wave_sum(s);
;         if (F.lane < 16) F.ssqh()[(size_t)row * 16 + F.lane] = F.lane == 0 ? s : 0.f;
;     }
.LBB0_2080:
	v_readlane_b32 s16, v254, 24
	v_readlane_b32 s17, v254, 25
	v_readlane_b32 s44, v254, 22
	v_readlane_b32 s45, v254, 23
	v_readlane_b32 s10, v254, 20
	v_readlane_b32 s11, v254, 21
	v_lshl_add_u64 v[32:33], s[76:77], 0, v[6:7]
	s_mov_b32 s24, 0xcd10000
	s_mov_b32 s25, 0
	v_lshl_add_u64 v[32:33], v[32:33], 0, s[24:25]
	v_lshl_add_u64 v[210:211], s[76:77], 0, v[4:5]
	global_load_dwordx4 v[36:39], v[8:9], off offset:-3072
	global_load_dwordx4 v[40:43], v[8:9], off offset:-2048
	global_load_dwordx4 v[44:47], v[8:9], off offset:-1024
	global_load_dwordx4 v[48:51], v[8:9], off
	v_lshl_add_u64 v[8:9], v[8:9], 0, s[16:17]
	global_load_dwordx4 v[52:55], v[8:9], off offset:-3072
	global_load_dwordx4 v[56:59], v[8:9], off offset:-2048
	global_load_dwordx4 v[60:63], v[8:9], off offset:-1024
	global_load_dwordx4 v[64:67], v[8:9], off
	v_lshl_add_u64 v[8:9], v[8:9], 0, s[16:17]
	global_load_dwordx4 v[68:71], v[8:9], off offset:-3072
	global_load_dwordx4 v[72:75], v[8:9], off offset:-2048
	global_load_dwordx4 v[76:79], v[8:9], off offset:-1024
	global_load_dwordx4 v[80:83], v[8:9], off
	v_lshl_add_u64 v[8:9], v[8:9], 0, s[16:17]
	global_load_dwordx4 v[84:87], v[8:9], off offset:-3072
	global_load_dwordx4 v[88:91], v[8:9], off offset:-2048
	global_load_dwordx4 v[92:95], v[8:9], off offset:-1024
	global_load_dwordx4 v[96:99], v[8:9], off
	v_lshl_add_u64 v[8:9], v[8:9], 0, s[16:17]
	global_load_dwordx4 v[100:103], v[8:9], off offset:-3072
	global_load_dwordx4 v[104:107], v[8:9], off offset:-2048
	global_load_dwordx4 v[108:111], v[8:9], off offset:-1024
	global_load_dwordx4 v[112:115], v[8:9], off
	v_lshl_add_u64 v[8:9], v[8:9], 0, s[16:17]
	global_load_dwordx4 v[116:119], v[8:9], off offset:-3072
	global_load_dwordx4 v[120:123], v[8:9], off offset:-2048
	global_load_dwordx4 v[124:127], v[8:9], off offset:-1024
	global_load_dwordx4 v[128:131], v[8:9], off
	v_lshl_add_u64 v[8:9], v[8:9], 0, s[16:17]
	global_load_dwordx4 v[132:135], v[8:9], off offset:-3072
	global_load_dwordx4 v[188:191], v[8:9], off offset:-2048
	global_load_dwordx4 v[192:195], v[8:9], off offset:-1024
	global_load_dwordx4 v[196:199], v[8:9], off
	v_lshl_add_u64 v[8:9], v[8:9], 0, s[16:17]
	global_load_dwordx4 v[200:203], v[8:9], off offset:-3072
	global_load_dwordx4 v[204:207], v[8:9], off offset:-2048
	global_load_dwordx4 v[236:239], v[8:9], off offset:-1024
	global_load_dwordx4 v[240:243], v[8:9], off
	s_waitcnt vmcnt(28)
	v_mul_f32_e32 v0, v37, v37
	v_mul_f32_e32 v3, v39, v39
	v_fmac_f32_e32 v0, v36, v36
	v_fmac_f32_e32 v3, v38, v38
	v_add_f32_e32 v16, v0, v3
	v_mul_f32_e32 v0, v41, v41
	v_mul_f32_e32 v3, v43, v43
	v_fmac_f32_e32 v0, v40, v40
	v_fmac_f32_e32 v3, v42, v42
	v_add_f32_e32 v0, v0, v3
	v_add_f32_e32 v16, v16, v0
	v_mul_f32_e32 v0, v45, v45
	v_mul_f32_e32 v3, v47, v47
	v_fmac_f32_e32 v0, v44, v44
	v_fmac_f32_e32 v3, v46, v46
	v_add_f32_e32 v0, v0, v3
	v_add_f32_e32 v16, v16, v0
	v_mul_f32_e32 v0, v49, v49
	v_mul_f32_e32 v3, v51, v51
	v_fmac_f32_e32 v0, v48, v48
	v_fmac_f32_e32 v3, v50, v50
	v_add_f32_e32 v0, v0, v3
	v_add_f32_e32 v16, v16, v0
	v_cvt_pk_bf16_f32 v36, v36, v37
	v_cvt_pk_bf16_f32 v37, v38, v39
	v_cvt_pk_bf16_f32 v40, v40, v41
	v_cvt_pk_bf16_f32 v41, v42, v43
	v_cvt_pk_bf16_f32 v44, v44, v45
	v_cvt_pk_bf16_f32 v45, v46, v47
	v_cvt_pk_bf16_f32 v48, v48, v49
	v_cvt_pk_bf16_f32 v49, v50, v51
	global_store_dwordx2 v[32:33], v[36:37], off
	global_store_dwordx2 v[32:33], v[40:41], off offset:512
	global_store_dwordx2 v[32:33], v[44:45], off offset:1024
	global_store_dwordx2 v[32:33], v[48:49], off offset:1536
	v_lshl_add_u64 v[32:33], v[32:33], 0, s[44:45]
	s_waitcnt vmcnt(28)
	v_mul_f32_e32 v0, v53, v53
	v_mul_f32_e32 v3, v55, v55
	v_fmac_f32_e32 v0, v52, v52
	v_fmac_f32_e32 v3, v54, v54
	v_add_f32_e32 v17, v0, v3
	v_mul_f32_e32 v0, v57, v57
	v_mul_f32_e32 v3, v59, v59
	v_fmac_f32_e32 v0, v56, v56
	v_fmac_f32_e32 v3, v58, v58
	v_add_f32_e32 v0, v0, v3
	v_add_f32_e32 v17, v17, v0
	v_mul_f32_e32 v0, v61, v61
	v_mul_f32_e32 v3, v63, v63
	v_fmac_f32_e32 v0, v60, v60
	v_fmac_f32_e32 v3, v62, v62
	v_add_f32_e32 v0, v0, v3
	v_add_f32_e32 v17, v17, v0
	v_mul_f32_e32 v0, v65, v65
	v_mul_f32_e32 v3, v67, v67
	v_fmac_f32_e32 v0, v64, v64
	v_fmac_f32_e32 v3, v66, v66
	v_add_f32_e32 v0, v0, v3
	v_add_f32_e32 v17, v17, v0
	v_cvt_pk_bf16_f32 v52, v52, v53
	v_cvt_pk_bf16_f32 v53, v54, v55
	v_cvt_pk_bf16_f32 v56, v56, v57
	v_cvt_pk_bf16_f32 v57, v58, v59
	v_cvt_pk_bf16_f32 v60, v60, v61
	v_cvt_pk_bf16_f32 v61, v62, v63
	v_cvt_pk_bf16_f32 v64, v64, v65
	v_cvt_pk_bf16_f32 v65, v66, v67
	global_store_dwordx2 v[32:33], v[52:53], off
	global_store_dwordx2 v[32:33], v[56:57], off offset:512
	global_store_dwordx2 v[32:33], v[60:61], off offset:1024
	global_store_dwordx2 v[32:33], v[64:65], off offset:1536
	v_lshl_add_u64 v[32:33], v[32:33], 0, s[44:45]
	s_waitcnt vmcnt(28)
	v_mul_f32_e32 v0, v69, v69
	v_mul_f32_e32 v3, v71, v71
	v_fmac_f32_e32 v0, v68, v68
	v_fmac_f32_e32 v3, v70, v70
	v_add_f32_e32 v18, v0, v3
	v_mul_f32_e32 v0, v73, v73
	v_mul_f32_e32 v3, v75, v75
	v_fmac_f32_e32 v0, v72, v72
	v_fmac_f32_e32 v3, v74, v74
	v_add_f32_e32 v0, v0, v3
	v_add_f32_e32 v18, v18, v0
	v_mul_f32_e32 v0, v77, v77
	v_mul_f32_e32 v3, v79, v79
	v_fmac_f32_e32 v0, v76, v76
	v_fmac_f32_e32 v3, v78, v78
	v_add_f32_e32 v0, v0, v3
	v_add_f32_e32 v18, v18, v0
	v_mul_f32_e32 v0, v81, v81
	v_mul_f32_e32 v3, v83, v83
	v_fmac_f32_e32 v0, v80, v80
	v_fmac_f32_e32 v3, v82, v82
	v_add_f32_e32 v0, v0, v3
	v_add_f32_e32 v18, v18, v0
	v_cvt_pk_bf16_f32 v68, v68, v69
	v_cvt_pk_bf16_f32 v69, v70, v71
	v_cvt_pk_bf16_f32 v72, v72, v73
	v_cvt_pk_bf16_f32 v73, v74, v75
	v_cvt_pk_bf16_f32 v76, v76, v77
	v_cvt_pk_bf16_f32 v77, v78, v79
	v_cvt_pk_bf16_f32 v80, v80, v81
	v_cvt_pk_bf16_f32 v81, v82, v83
	global_store_dwordx2 v[32:33], v[68:69], off
	global_store_dwordx2 v[32:33], v[72:73], off offset:512
	global_store_dwordx2 v[32:33], v[76:77], off offset:1024
	global_store_dwordx2 v[32:33], v[80:81], off offset:1536
	v_lshl_add_u64 v[32:33], v[32:33], 0, s[44:45]
	s_waitcnt vmcnt(28)
; DI void st_bf4(bf16_t* p, f32x4 v) { u32x2 w; w.x = pk2(v[0], v[1]); w.y = pk2(v[2], v[3]); *(u32x2*)p = w; }
;     DI bf16_t* hb() const { return (bf16_t*)(ws + WS_HB); }
;     DI float* ssqh() const { return (float*)(ws + WS_SSQH); }
;     DI const float* gin(int i) const { return (const float*)(const __attribute__((address_space(1))) float*)kp->in[i]; }
; DI void phase_prep(Frame& F) {
;     ...
;     for (int row = F.gw; row < M; row += F.ngw) {
;         const f32x4* xr = (const f32x4*)(F.gin(0) + (size_t)row * DM) + F.lane; float s = 0.f;
; #pragma unroll
;         for (int j = 0; j < 4; ++j) { f32x4 v = xr[64 * j]; s += (v[0] * v[0] + v[1] * v[1]) + (v[2] * v[2] + v[3] * v[3]);
;             st_bf4(F.hb() + (size_t)row * DM + 4 * (F.lane + 64 * j), v); }
;         s = wave_sum(s);
;         if (F.lane < 16) F.ssqh()[(size_t)row * 16 + F.lane] = F.lane == 0 ? s : 0.f;
	v_mul_f32_e32 v0, v85, v85
	v_mul_f32_e32 v3, v87, v87
	v_fmac_f32_e32 v0, v84, v84
	v_fmac_f32_e32 v3, v86, v86
	v_add_f32_e32 v19, v0, v3
	v_mul_f32_e32 v0, v89, v89
	v_mul_f32_e32 v3, v91, v91
	v_fmac_f32_e32 v0, v88, v88
	v_fmac_f32_e32 v3, v90, v90
	v_add_f32_e32 v0, v0, v3
	v_add_f32_e32 v19, v19, v0
	v_mul_f32_e32 v0, v93, v93
	v_mul_f32_e32 v3, v95, v95
	v_fmac_f32_e32 v0, v92, v92
	v_fmac_f32_e32 v3, v94, v94
	v_add_f32_e32 v0, v0, v3
	v_add_f32_e32 v19, v19, v0
	v_mul_f32_e32 v0, v97, v97
	v_mul_f32_e32 v3, v99, v99
	v_fmac_f32_e32 v0, v96, v96
	v_fmac_f32_e32 v3, v98, v98
	v_add_f32_e32 v0, v0, v3
	v_add_f32_e32 v19, v19, v0
	v_cvt_pk_bf16_f32 v84, v84, v85
	v_cvt_pk_bf16_f32 v85, v86, v87
	v_cvt_pk_bf16_f32 v88, v88, v89
	v_cvt_pk_bf16_f32 v89, v90, v91
	v_cvt_pk_bf16_f32 v92, v92, v93
	v_cvt_pk_bf16_f32 v93, v94, v95
	v_cvt_pk_bf16_f32 v96, v96, v97
	v_cvt_pk_bf16_f32 v97, v98, v99
	global_store_dwordx2 v[32:33], v[84:85], off
	global_store_dwordx2 v[32:33], v[88:89], off offset:512
	global_store_dwordx2 v[32:33], v[92:93], off offset:1024
	global_store_dwordx2 v[32:33], v[96:97], off offset:1536
	v_lshl_add_u64 v[32:33], v[32:33], 0, s[44:45]
	s_waitcnt vmcnt(28)
	v_mul_f32_e32 v0, v101, v101
	v_mul_f32_e32 v3, v103, v103
	v_fmac_f32_e32 v0, v100, v100
	v_fmac_f32_e32 v3, v102, v102
	v_add_f32_e32 v20, v0, v3
	v_mul_f32_e32 v0, v105, v105
	v_mul_f32_e32 v3, v107, v107
	v_fmac_f32_e32 v0, v104, v104
	v_fmac_f32_e32 v3, v106, v106
	v_add_f32_e32 v0, v0, v3
	v_add_f32_e32 v20, v20, v0
	v_mul_f32_e32 v0, v109, v109
	v_mul_f32_e32 v3, v111, v111
	v_fmac_f32_e32 v0, v108, v108
	v_fmac_f32_e32 v3, v110, v110
	v_add_f32_e32 v0, v0, v3
	v_add_f32_e32 v20, v20, v0
	v_mul_f32_e32 v0, v113, v113
	v_mul_f32_e32 v3, v115, v115
	v_fmac_f32_e32 v0, v112, v112
	v_fmac_f32_e32 v3, v114, v114
	v_add_f32_e32 v0, v0, v3
	v_add_f32_e32 v20, v20, v0
	v_cvt_pk_bf16_f32 v100, v100, v101
	v_cvt_pk_bf16_f32 v101, v102, v103
	v_cvt_pk_bf16_f32 v104, v104, v105
	v_cvt_pk_bf16_f32 v105, v106, v107
	v_cvt_pk_bf16_f32 v108, v108, v109
	v_cvt_pk_bf16_f32 v109, v110, v111
	v_cvt_pk_bf16_f32 v112, v112, v113
	v_cvt_pk_bf16_f32 v113, v114, v115
	global_store_dwordx2 v[32:33], v[100:101], off
	global_store_dwordx2 v[32:33], v[104:105], off offset:512
	global_store_dwordx2 v[32:33], v[108:109], off offset:1024
	global_store_dwordx2 v[32:33], v[112:113], off offset:1536
	v_lshl_add_u64 v[32:33], v[32:33], 0, s[44:45]
	s_waitcnt vmcnt(28)
	v_mul_f32_e32 v0, v117, v117
	v_mul_f32_e32 v3, v119, v119
	v_fmac_f32_e32 v0, v116, v116
	v_fmac_f32_e32 v3, v118, v118
	v_add_f32_e32 v21, v0, v3
	v_mul_f32_e32 v0, v121, v121
	v_mul_f32_e32 v3, v123, v123
	v_fmac_f32_e32 v0, v120, v120
	v_fmac_f32_e32 v3, v122, v122
	v_add_f32_e32 v0, v0, v3
	v_add_f32_e32 v21, v21, v0
	v_mul_f32_e32 v0, v125, v125
	v_mul_f32_e32 v3, v127, v127
	v_fmac_f32_e32 v0, v124, v124
	v_fmac_f32_e32 v3, v126, v126
	v_add_f32_e32 v0, v0, v3
	v_add_f32_e32 v21, v21, v0
	v_mul_f32_e32 v0, v129, v129
	v_mul_f32_e32 v3, v131, v131
	v_fmac_f32_e32 v0, v128, v128
	v_fmac_f32_e32 v3, v130, v130
	v_add_f32_e32 v0, v0, v3
	v_add_f32_e32 v21, v21, v0
	v_cvt_pk_bf16_f32 v116, v116, v117
	v_cvt_pk_bf16_f32 v117, v118, v119
	v_cvt_pk_bf16_f32 v120, v120, v121
	v_cvt_pk_bf16_f32 v121, v122, v123
	v_cvt_pk_bf16_f32 v124, v124, v125
	v_cvt_pk_bf16_f32 v125, v126, v127
	v_cvt_pk_bf16_f32 v128, v128, v129
	v_cvt_pk_bf16_f32 v129, v130, v131
	global_store_dwordx2 v[32:33], v[116:117], off
	global_store_dwordx2 v[32:33], v[120:121], off offset:512
	global_store_dwordx2 v[32:33], v[124:125], off offset:1024
	global_store_dwordx2 v[32:33], v[128:129], off offset:1536
	v_lshl_add_u64 v[32:33], v[32:33], 0, s[44:45]
	s_waitcnt vmcnt(28)
	v_mul_f32_e32 v0, v133, v133
	v_mul_f32_e32 v3, v135, v135
	v_fmac_f32_e32 v0, v132, v132
	v_fmac_f32_e32 v3, v134, v134
	v_add_f32_e32 v22, v0, v3
	v_mul_f32_e32 v0, v189, v189
	v_mul_f32_e32 v3, v191, v191
	v_fmac_f32_e32 v0, v188, v188
	v_fmac_f32_e32 v3, v190, v190
	v_add_f32_e32 v0, v0, v3
	v_add_f32_e32 v22, v22, v0
	v_mul_f32_e32 v0, v193, v193
	v_mul_f32_e32 v3, v195, v195
	v_fmac_f32_e32 v0, v192, v192
	v_fmac_f32_e32 v3, v194, v194
	v_add_f32_e32 v0, v0, v3
	v_add_f32_e32 v22, v22, v0
	v_mul_f32_e32 v0, v197, v197
	v_mul_f32_e32 v3, v199, v199
	v_fmac_f32_e32 v0, v196, v196
	v_fmac_f32_e32 v3, v198, v198
	v_add_f32_e32 v0, v0, v3
	v_add_f32_e32 v22, v22, v0
	v_cvt_pk_bf16_f32 v132, v132, v133
	v_cvt_pk_bf16_f32 v133, v134, v135
	v_cvt_pk_bf16_f32 v188, v188, v189
	v_cvt_pk_bf16_f32 v189, v190, v191
	v_cvt_pk_bf16_f32 v192, v192, v193
	v_cvt_pk_bf16_f32 v193, v194, v195
	v_cvt_pk_bf16_f32 v196, v196, v197
	v_cvt_pk_bf16_f32 v197, v198, v199
	global_store_dwordx2 v[32:33], v[132:133], off
	global_store_dwordx2 v[32:33], v[188:189], off offset:512
	global_store_dwordx2 v[32:33], v[192:193], off offset:1024
	global_store_dwordx2 v[32:33], v[196:197], off offset:1536
	v_lshl_add_u64 v[32:33], v[32:33], 0, s[44:45]
	s_waitcnt vmcnt(28)
; DI void st_bf4(bf16_t* p, f32x4 v) { u32x2 w; w.x = pk2(v[0], v[1]); w.y = pk2(v[2], v[3]); *(u32x2*)p = w; }
;     DI bf16_t* hb() const { return (bf16_t*)(ws + WS_HB); }
;     DI float* ssqh() const { return (float*)(ws + WS_SSQH); }
;     DI const float* gin(int i) const { return (const float*)(const __attribute__((address_space(1))) float*)kp->in[i]; }
; DI float wave_sum(float v) {
; #pragma unroll
;     for (int o = 1; o < 64; o <<= 1) v += __shfl_xor(v, o);
;     return v;
; }
; DI void phase_prep(Frame& F) {
;     ...
;     for (int row = F.gw; row < M; row += F.ngw) {
;         const f32x4* xr = (const f32x4*)(F.gin(0) + (size_t)row * DM) + F.lane; float s = 0.f;
; #pragma unroll
;         for (int j = 0; j < 4; ++j) { f32x4 v = xr[64 * j]; s += (v[0] * v[0] + v[1] * v[1]) + (v[2] * v[2] + v[3] * v[3]);
;             st_bf4(F.hb() + (size_t)row * DM + 4 * (F.lane + 64 * j), v); }
;         s = wave_sum(s);
;         if (F.lane < 16) F.ssqh()[(size_t)row * 16 + F.lane] = F.lane == 0 ? s : 0.f;
	v_mul_f32_e32 v0, v201, v201
	v_mul_f32_e32 v3, v203, v203
	v_fmac_f32_e32 v0, v200, v200
	v_fmac_f32_e32 v3, v202, v202
	v_add_f32_e32 v23, v0, v3
	v_mul_f32_e32 v0, v205, v205
	v_mul_f32_e32 v3, v207, v207
	v_fmac_f32_e32 v0, v204, v204
	v_fmac_f32_e32 v3, v206, v206
	v_add_f32_e32 v0, v0, v3
	v_add_f32_e32 v23, v23, v0
	v_mul_f32_e32 v0, v237, v237
	v_mul_f32_e32 v3, v239, v239
	v_fmac_f32_e32 v0, v236, v236
	v_fmac_f32_e32 v3, v238, v238
	v_add_f32_e32 v0, v0, v3
	v_add_f32_e32 v23, v23, v0
	v_mul_f32_e32 v0, v241, v241
	v_mul_f32_e32 v3, v243, v243
	v_fmac_f32_e32 v0, v240, v240
	v_fmac_f32_e32 v3, v242, v242
	v_add_f32_e32 v0, v0, v3
	v_add_f32_e32 v23, v23, v0
	v_cvt_pk_bf16_f32 v200, v200, v201
	v_cvt_pk_bf16_f32 v201, v202, v203
	v_cvt_pk_bf16_f32 v204, v204, v205
	v_cvt_pk_bf16_f32 v205, v206, v207
	v_cvt_pk_bf16_f32 v236, v236, v237
	v_cvt_pk_bf16_f32 v237, v238, v239
	v_cvt_pk_bf16_f32 v240, v240, v241
	v_cvt_pk_bf16_f32 v241, v242, v243
	global_store_dwordx2 v[32:33], v[200:201], off
	global_store_dwordx2 v[32:33], v[204:205], off offset:512
	global_store_dwordx2 v[32:33], v[236:237], off offset:1024
	global_store_dwordx2 v[32:33], v[240:241], off offset:1536
	ds_bpermute_b32 v24, v10, v16
	ds_bpermute_b32 v25, v10, v17
	ds_bpermute_b32 v26, v10, v18
	ds_bpermute_b32 v27, v10, v19
	ds_bpermute_b32 v28, v10, v20
	ds_bpermute_b32 v29, v10, v21
	ds_bpermute_b32 v30, v10, v22
	ds_bpermute_b32 v31, v10, v23
	s_waitcnt lgkmcnt(0)
	v_add_f32_e32 v16, v16, v24
	v_add_f32_e32 v17, v17, v25
	v_add_f32_e32 v18, v18, v26
	v_add_f32_e32 v19, v19, v27
	v_add_f32_e32 v20, v20, v28
	v_add_f32_e32 v21, v21, v29
	v_add_f32_e32 v22, v22, v30
	v_add_f32_e32 v23, v23, v31
	ds_bpermute_b32 v24, v11, v16
	ds_bpermute_b32 v25, v11, v17
	ds_bpermute_b32 v26, v11, v18
	ds_bpermute_b32 v27, v11, v19
	ds_bpermute_b32 v28, v11, v20
	ds_bpermute_b32 v29, v11, v21
	ds_bpermute_b32 v30, v11, v22
	ds_bpermute_b32 v31, v11, v23
	s_waitcnt lgkmcnt(0)
	v_add_f32_e32 v16, v16, v24
	v_add_f32_e32 v17, v17, v25
	v_add_f32_e32 v18, v18, v26
	v_add_f32_e32 v19, v19, v27
	v_add_f32_e32 v20, v20, v28
	v_add_f32_e32 v21, v21, v29
	v_add_f32_e32 v22, v22, v30
	v_add_f32_e32 v23, v23, v31
	ds_bpermute_b32 v24, v12, v16
	ds_bpermute_b32 v25, v12, v17
	ds_bpermute_b32 v26, v12, v18
	ds_bpermute_b32 v27, v12, v19
	ds_bpermute_b32 v28, v12, v20
	ds_bpermute_b32 v29, v12, v21
	ds_bpermute_b32 v30, v12, v22
	ds_bpermute_b32 v31, v12, v23
	s_waitcnt lgkmcnt(0)
	v_add_f32_e32 v16, v16, v24
	v_add_f32_e32 v17, v17, v25
	v_add_f32_e32 v18, v18, v26
	v_add_f32_e32 v19, v19, v27
	v_add_f32_e32 v20, v20, v28
	v_add_f32_e32 v21, v21, v29
	v_add_f32_e32 v22, v22, v30
	v_add_f32_e32 v23, v23, v31
	ds_bpermute_b32 v24, v13, v16
	ds_bpermute_b32 v25, v13, v17
	ds_bpermute_b32 v26, v13, v18
	ds_bpermute_b32 v27, v13, v19
	ds_bpermute_b32 v28, v13, v20
	ds_bpermute_b32 v29, v13, v21
	ds_bpermute_b32 v30, v13, v22
	ds_bpermute_b32 v31, v13, v23
	s_waitcnt lgkmcnt(0)
	v_add_f32_e32 v16, v16, v24
	v_add_f32_e32 v17, v17, v25
	v_add_f32_e32 v18, v18, v26
	v_add_f32_e32 v19, v19, v27
	v_add_f32_e32 v20, v20, v28
	v_add_f32_e32 v21, v21, v29
	v_add_f32_e32 v22, v22, v30
	v_add_f32_e32 v23, v23, v31
	ds_bpermute_b32 v24, v14, v16
	ds_bpermute_b32 v25, v14, v17
	ds_bpermute_b32 v26, v14, v18
	ds_bpermute_b32 v27, v14, v19
	ds_bpermute_b32 v28, v14, v20
	ds_bpermute_b32 v29, v14, v21
	ds_bpermute_b32 v30, v14, v22
	ds_bpermute_b32 v31, v14, v23
	s_waitcnt lgkmcnt(0)
	v_add_f32_e32 v16, v16, v24
	v_add_f32_e32 v17, v17, v25
	v_add_f32_e32 v18, v18, v26
	v_add_f32_e32 v19, v19, v27
	v_add_f32_e32 v20, v20, v28
	v_add_f32_e32 v21, v21, v29
	v_add_f32_e32 v22, v22, v30
	v_add_f32_e32 v23, v23, v31
	ds_bpermute_b32 v24, v15, v16
	ds_bpermute_b32 v25, v15, v17
	ds_bpermute_b32 v26, v15, v18
	ds_bpermute_b32 v27, v15, v19
	ds_bpermute_b32 v28, v15, v20
	ds_bpermute_b32 v29, v15, v21
	ds_bpermute_b32 v30, v15, v22
	ds_bpermute_b32 v31, v15, v23
	s_waitcnt lgkmcnt(0)
	v_add_f32_e32 v16, v16, v24
	v_add_f32_e32 v17, v17, v25
	v_add_f32_e32 v18, v18, v26
	v_add_f32_e32 v19, v19, v27
	v_add_f32_e32 v20, v20, v28
	v_add_f32_e32 v21, v21, v29
	v_add_f32_e32 v22, v22, v30
	v_add_f32_e32 v23, v23, v31
	v_cndmask_b32_e64 v16, 0, v16, s[42:43]
	v_cndmask_b32_e64 v17, 0, v17, s[42:43]
	v_cndmask_b32_e64 v18, 0, v18, s[42:43]
	v_cndmask_b32_e64 v19, 0, v19, s[42:43]
	v_cndmask_b32_e64 v20, 0, v20, s[42:43]
	v_cndmask_b32_e64 v21, 0, v21, s[42:43]
	v_cndmask_b32_e64 v22, 0, v22, s[42:43]
	v_cndmask_b32_e64 v23, 0, v23, s[42:43]
	s_and_saveexec_b64 s[24:25], vcc
	global_store_dword v[210:211], v16, off
	v_lshl_add_u64 v[210:211], v[210:211], 0, s[10:11]
	global_store_dword v[210:211], v17, off
	v_lshl_add_u64 v[210:211], v[210:211], 0, s[10:11]
	global_store_dword v[210:211], v18, off
	v_lshl_add_u64 v[210:211], v[210:211], 0, s[10:11]
	global_store_dword v[210:211], v19, off
	v_lshl_add_u64 v[210:211], v[210:211], 0, s[10:11]
	global_store_dword v[210:211], v20, off
	v_lshl_add_u64 v[210:211], v[210:211], 0, s[10:11]
	global_store_dword v[210:211], v21, off
	v_lshl_add_u64 v[210:211], v[210:211], 0, s[10:11]
	global_store_dword v[210:211], v22, off
	v_lshl_add_u64 v[210:211], v[210:211], 0, s[10:11]
	global_store_dword v[210:211], v23, off
	s_or_b64 exec, exec, s[24:25]
